# GEMM K-loop: loop-invariant LDS read base addresses hoisted to per-tile registers (8 VALU adds per iteration pair removed)
# baseline (speedup 1.0000x reference)
; #define PG8_STAGE(bufoff, gbase, voff) do { _Pragma("unroll") for (int _i = 0; _i < 2; ++_i) \
;         __builtin_amdgcn_global_load_lds((const unsigned*)((const char*)(gbase) + (voff)[_i]), (PG8_LAS unsigned*)(lds + (bufoff) + ldsw + _i * 8192), 16, 0, 0); } while (0)
; #define PG8_LDA(dst, b, h) do { _Pragma("unroll") for (int m = 0; m < 4; ++m) _Pragma("unroll") for (int k = 0; k < 2; ++k) dst[m][k] = *(const PG8_LAS bf16x8*)(lds + PG8_SA(b, h) + aoff + m * 2048 + k * 1024); } while (0)
; #define PG8_LDB(dst, b, h) do { _Pragma("unroll") for (int n = 0; n < 2; ++n) _Pragma("unroll") for (int k = 0; k < 2; ++k) dst[n][k] = *(const PG8_LAS bf16x8*)(lds + PG8_SB(b, h) + boff + n * 2048 + k * 1024); } while (0)
; #define PG8_MMA(ai, bj, At, Bt) do { __builtin_amdgcn_s_setprio(1); _Pragma("unroll") for (int m = 0; m < 4; ++m) _Pragma("unroll") for (int n = 0; n < 2; ++n) _Pragma("unroll") for (int k = 0; k < 2; ++k) \
;         acc[ai][bj][m][n] = __builtin_amdgcn_mfma_f32_16x16x32_bf16(Bt[n][k], At[m][k], acc[ai][bj][m][n], 0, 0, 0); __builtin_amdgcn_s_setprio(0); } while (0)
; #define PG8_BAR __builtin_amdgcn_s_barrier()
; template <class Epi, class Sched, bool STAMP = false>
; __device__ __forceinline__ void gemm_phase(PG8_LAS unsigned char* lds, const Gemm g, const Sched& S, const Epi& E, unsigned long long* stamps) {
;     ...
;         for (int t = 0; t < nt; t += 2) {
;             const bool last = (t == nt - 2);
;             const char* a1 = cA + (size_t)(t + 1) * kstep;
;             const char* a2 = last ? nA : cA + (size_t)(t + 2) * kstep; const char* b2 = last ? nB : cB + (size_t)(t + 2) * kstep;
;             const char* a3 = a2 + kstep; const char* b3 = b2 + kstep;
;             if (last && has_next) S.a_ready(nxt);
;             PG8_LDB(B0, 0, 0); PG8_SCHED; PG8_LDA(At, 0, 0); PG8_STAGE(PG8_SA(1, 1), a1 + hstep, voffA);
;             PG8_WAIT_L(8); PG8_BAR; PG8_WAIT_L(0); PG8_MMA(0, 0, At, B0); PG8_BAR; PG8_SCHED;
;             PG8_LDB(B1, 0, 1); PG8_STAGE(PG8_SB(0, 0), b2, voffB);
;             PG8_BAR; PG8_WAIT_L(0); PG8_MMA(0, 1, At, B1); PG8_BAR;
;             PG8_LDA(At, 0, 1); PG8_STAGE(PG8_SA(0, 0), a2, voffA);
;             PG8_BAR; PG8_WAIT_L(0); PG8_MMA(1, 0, At, B0); PG8_BAR; PG8_SCHED;
;             PG8_STAGE(PG8_SB(0, 1), b2 + hstep, voffB);
;             PG8_WAIT_V(6); PG8_BAR; PG8_MMA(1, 1, At, B1); PG8_BAR;
.LBB0_744:
	s_add_u32 s0, s22, 0x80
	s_addc_u32 s1, s23, 0
	s_add_u32 s88, s88, 0x100
	s_addc_u32 s89, s89, 0
	s_mov_b32 s22, 0
	v_add_u32_e32 v240, 0x10000, v217
	v_add_u32_e32 v241, 0x14000, v217
	v_add_u32_e32 v242, 0x18000, v217
	v_add_u32_e32 v243, s35, v217
.Lg_peel:
	s_add_i32 s93, s22, 2
	s_add_u32 s38, s0, 0x80
	s_addc_u32 s23, s1, 0
	s_add_i32 s62, 0, 0x10000
	ds_read_b128 v[130:133], v240
	ds_read_b128 v[134:137], v240 offset:1024
	ds_read_b128 v[138:141], v240 offset:2048
	ds_read_b128 v[142:145], v240 offset:3072
	s_cmp_eq_u32 s4, s22
	s_cselect_b32 s22, s90, s38
	s_cselect_b32 s23, s91, s23
	s_cselect_b32 s39, s31, s89
	s_cselect_b32 s38, s30, s88
	s_add_i32 m0, s80, 0xc000
	ds_read_b128 v[146:149], v218
	ds_read_b128 v[150:153], v218 offset:1024
	ds_read_b128 v[154:157], v218 offset:2048
	ds_read_b128 v[158:161], v218 offset:3072
	ds_read_b128 v[176:179], v218 offset:4096
	ds_read_b128 v[180:183], v218 offset:5120
	ds_read_b128 v[184:187], v218 offset:6144
	ds_read_b128 v[188:191], v218 offset:7168
	global_load_lds_dwordx4 v172, s[0:1]
	s_add_i32 m0, s80, 0xe000
	s_nop 0
	global_load_lds_dwordx4 v174, s[0:1]
	s_waitcnt lgkmcnt(8)
	s_barrier
	s_waitcnt lgkmcnt(0)
	v_mfma_f32_16x16x32_bf16 v[126:129], v[130:133], v[146:149], 0
	v_mfma_f32_16x16x32_bf16 v[122:125], v[138:141], v[146:149], 0
	v_mfma_f32_16x16x32_bf16 v[118:121], v[130:133], v[154:157], 0
	v_mfma_f32_16x16x32_bf16 v[114:117], v[138:141], v[154:157], 0
	v_mfma_f32_16x16x32_bf16 v[102:105], v[130:133], v[176:179], 0
	v_mfma_f32_16x16x32_bf16 v[98:101], v[138:141], v[176:179], 0
	v_mfma_f32_16x16x32_bf16 v[86:89], v[130:133], v[184:187], 0
	v_mfma_f32_16x16x32_bf16 v[82:85], v[138:141], v[184:187], 0
	v_mfma_f32_16x16x32_bf16 v[126:129], v[134:137], v[150:153], v[126:129]
	v_mfma_f32_16x16x32_bf16 v[122:125], v[142:145], v[150:153], v[122:125]
	v_mfma_f32_16x16x32_bf16 v[118:121], v[134:137], v[158:161], v[118:121]
	v_mfma_f32_16x16x32_bf16 v[114:117], v[142:145], v[158:161], v[114:117]
	v_mfma_f32_16x16x32_bf16 v[102:105], v[134:137], v[180:183], v[102:105]
	v_mfma_f32_16x16x32_bf16 v[98:101], v[142:145], v[180:183], v[98:101]
	v_mfma_f32_16x16x32_bf16 v[86:89], v[134:137], v[188:191], v[86:89]
	v_mfma_f32_16x16x32_bf16 v[82:85], v[142:145], v[188:191], v[82:85]
	s_barrier
	s_add_i32 s63, 0, 0x14000
	s_add_i32 s62, s62, s79
	s_add_u32 s98, s38, s10
	s_addc_u32 s99, s39, s11
	s_mov_b32 m0, s62
	ds_read_b128 v[192:195], v241
	ds_read_b128 v[196:199], v241 offset:1024
	ds_read_b128 v[200:203], v241 offset:2048
	ds_read_b128 v[204:207], v241 offset:3072
	global_load_lds_dwordx4 v164, s[38:39]
	s_add_i32 m0, s62, 0x2000
	s_nop 0
	global_load_lds_dwordx4 v170, s[38:39]
	s_barrier
	s_waitcnt lgkmcnt(0)
	v_mfma_f32_16x16x32_bf16 v[110:113], v[192:195], v[146:149], 0
	v_mfma_f32_16x16x32_bf16 v[106:109], v[200:203], v[146:149], 0
	v_mfma_f32_16x16x32_bf16 v[94:97], v[192:195], v[154:157], 0
	v_mfma_f32_16x16x32_bf16 v[90:93], v[200:203], v[154:157], 0
	v_mfma_f32_16x16x32_bf16 v[78:81], v[192:195], v[176:179], 0
	v_mfma_f32_16x16x32_bf16 v[74:77], v[200:203], v[176:179], 0
	v_mfma_f32_16x16x32_bf16 v[70:73], v[192:195], v[184:187], 0
	v_mfma_f32_16x16x32_bf16 v[66:69], v[200:203], v[184:187], 0
	v_mfma_f32_16x16x32_bf16 v[110:113], v[196:199], v[150:153], v[110:113]
	v_mfma_f32_16x16x32_bf16 v[106:109], v[204:207], v[150:153], v[106:109]
	v_mfma_f32_16x16x32_bf16 v[94:97], v[196:199], v[158:161], v[94:97]
	v_mfma_f32_16x16x32_bf16 v[90:93], v[204:207], v[158:161], v[90:93]
	v_mfma_f32_16x16x32_bf16 v[78:81], v[196:199], v[180:183], v[78:81]
	v_mfma_f32_16x16x32_bf16 v[74:77], v[204:207], v[180:183], v[74:77]
	v_mfma_f32_16x16x32_bf16 v[70:73], v[196:199], v[188:191], v[70:73]
	v_mfma_f32_16x16x32_bf16 v[66:69], v[204:207], v[188:191], v[66:69]
	s_mov_b32 m0, s80
	s_add_u32 s100, s22, s10
	s_addc_u32 s101, s23, s11
	s_barrier
	ds_read_b128 v[146:149], v218 offset:16384
	ds_read_b128 v[150:153], v218 offset:17408
	ds_read_b128 v[154:157], v218 offset:18432
	ds_read_b128 v[158:161], v218 offset:19456
	ds_read_b128 v[176:179], v218 offset:20480
	ds_read_b128 v[180:183], v218 offset:21504
	ds_read_b128 v[184:187], v218 offset:22528
	ds_read_b128 v[188:191], v218 offset:23552
	global_load_lds_dwordx4 v162, s[22:23]
	s_mov_b32 m0, s81
	s_nop 0
	global_load_lds_dwordx4 v166, s[22:23]
	s_barrier
	s_waitcnt lgkmcnt(0)
	v_mfma_f32_16x16x32_bf16 v[62:65], v[130:133], v[146:149], 0
	v_mfma_f32_16x16x32_bf16 v[58:61], v[138:141], v[146:149], 0
	v_mfma_f32_16x16x32_bf16 v[54:57], v[130:133], v[154:157], 0
	v_mfma_f32_16x16x32_bf16 v[50:53], v[138:141], v[154:157], 0
	v_mfma_f32_16x16x32_bf16 v[38:41], v[130:133], v[176:179], 0
	v_mfma_f32_16x16x32_bf16 v[34:37], v[138:141], v[176:179], 0
	v_mfma_f32_16x16x32_bf16 v[22:25], v[130:133], v[184:187], 0
	v_mfma_f32_16x16x32_bf16 v[18:21], v[138:141], v[184:187], 0
	v_mfma_f32_16x16x32_bf16 v[62:65], v[134:137], v[150:153], v[62:65]
	v_mfma_f32_16x16x32_bf16 v[58:61], v[142:145], v[150:153], v[58:61]
	v_mfma_f32_16x16x32_bf16 v[54:57], v[134:137], v[158:161], v[54:57]
	v_mfma_f32_16x16x32_bf16 v[50:53], v[142:145], v[158:161], v[50:53]
	v_mfma_f32_16x16x32_bf16 v[38:41], v[134:137], v[180:183], v[38:41]
	v_mfma_f32_16x16x32_bf16 v[34:37], v[142:145], v[180:183], v[34:37]
	v_mfma_f32_16x16x32_bf16 v[22:25], v[134:137], v[188:191], v[22:25]
	v_mfma_f32_16x16x32_bf16 v[18:21], v[142:145], v[188:191], v[18:21]
	s_barrier
	s_add_u32 s38, s38, s94
	s_addc_u32 s39, s39, 0
	s_add_i32 s62, s63, s79
	s_mov_b32 m0, s62
	global_load_lds_dwordx4 v164, s[38:39]
	s_add_i32 m0, s62, 0x2000
	s_nop 0
	global_load_lds_dwordx4 v170, s[38:39]
	s_waitcnt vmcnt(6)
	s_barrier
; #define PG8_STAGE(bufoff, gbase, voff) do { _Pragma("unroll") for (int _i = 0; _i < 2; ++_i) \
;         __builtin_amdgcn_global_load_lds((const unsigned*)((const char*)(gbase) + (voff)[_i]), (PG8_LAS unsigned*)(lds + (bufoff) + ldsw + _i * 8192), 16, 0, 0); } while (0)
; #define PG8_LDA(dst, b, h) do { _Pragma("unroll") for (int m = 0; m < 4; ++m) _Pragma("unroll") for (int k = 0; k < 2; ++k) dst[m][k] = *(const PG8_LAS bf16x8*)(lds + PG8_SA(b, h) + aoff + m * 2048 + k * 1024); } while (0)
; #define PG8_LDB(dst, b, h) do { _Pragma("unroll") for (int n = 0; n < 2; ++n) _Pragma("unroll") for (int k = 0; k < 2; ++k) dst[n][k] = *(const PG8_LAS bf16x8*)(lds + PG8_SB(b, h) + boff + n * 2048 + k * 1024); } while (0)
; #define PG8_MMA(ai, bj, At, Bt) do { __builtin_amdgcn_s_setprio(1); _Pragma("unroll") for (int m = 0; m < 4; ++m) _Pragma("unroll") for (int n = 0; n < 2; ++n) _Pragma("unroll") for (int k = 0; k < 2; ++k) \
;         acc[ai][bj][m][n] = __builtin_amdgcn_mfma_f32_16x16x32_bf16(Bt[n][k], At[m][k], acc[ai][bj][m][n], 0, 0, 0); __builtin_amdgcn_s_setprio(0); } while (0)
; #define PG8_WAIT_V(n) asm volatile("s_waitcnt vmcnt(" #n ")" ::: "memory")
; #define PG8_WAIT_L(n) asm volatile("s_waitcnt lgkmcnt(" #n ")" ::: "memory")
; #define PG8_BAR __builtin_amdgcn_s_barrier()
; #define PG8_SCHED __builtin_amdgcn_sched_barrier(0)
; template <class Epi, class Sched, bool STAMP = false>
; __device__ __forceinline__ void gemm_phase(PG8_LAS unsigned char* lds, const Gemm g, const Sched& S, const Epi& E, unsigned long long* stamps) {
;     ...
;             PG8_WAIT_V(6); PG8_BAR; PG8_MMA(1, 1, At, B1); PG8_BAR;
;             PG8_LDB(B0, 1, 0); PG8_SCHED; PG8_LDA(At, 1, 0); PG8_STAGE(PG8_SA(0, 1), a2 + hstep, voffA);
;             PG8_WAIT_L(8); PG8_BAR; PG8_WAIT_L(0); PG8_MMA(0, 0, At, B0); PG8_BAR; PG8_SCHED;
;             PG8_LDB(B1, 1, 1); PG8_STAGE(PG8_SB(1, 0), b3, voffB);
;             PG8_BAR; PG8_WAIT_L(0); PG8_MMA(0, 1, At, B1); PG8_BAR;
;             PG8_LDA(At, 1, 1); PG8_STAGE(PG8_SA(1, 0), a3, voffA);
;             PG8_BAR; PG8_WAIT_L(0); PG8_MMA(1, 0, At, B0); PG8_BAR; PG8_SCHED;
	v_mfma_f32_16x16x32_bf16 v[46:49], v[192:195], v[146:149], 0
	v_mfma_f32_16x16x32_bf16 v[42:45], v[200:203], v[146:149], 0
	v_mfma_f32_16x16x32_bf16 v[30:33], v[192:195], v[154:157], 0
	v_mfma_f32_16x16x32_bf16 v[26:29], v[200:203], v[154:157], 0
	v_mfma_f32_16x16x32_bf16 v[14:17], v[192:195], v[176:179], 0
	v_mfma_f32_16x16x32_bf16 v[10:13], v[200:203], v[176:179], 0
	v_mfma_f32_16x16x32_bf16 v[6:9], v[192:195], v[184:187], 0
	v_mfma_f32_16x16x32_bf16 v[2:5], v[200:203], v[184:187], 0
	v_mfma_f32_16x16x32_bf16 v[46:49], v[196:199], v[150:153], v[46:49]
	v_mfma_f32_16x16x32_bf16 v[42:45], v[204:207], v[150:153], v[42:45]
	v_mfma_f32_16x16x32_bf16 v[30:33], v[196:199], v[158:161], v[30:33]
	v_mfma_f32_16x16x32_bf16 v[26:29], v[204:207], v[158:161], v[26:29]
	v_mfma_f32_16x16x32_bf16 v[14:17], v[196:199], v[180:183], v[14:17]
	v_mfma_f32_16x16x32_bf16 v[10:13], v[204:207], v[180:183], v[10:13]
	v_mfma_f32_16x16x32_bf16 v[6:9], v[196:199], v[188:191], v[6:9]
	v_mfma_f32_16x16x32_bf16 v[2:5], v[204:207], v[188:191], v[2:5]
	s_add_i32 s38, 0, 0x18000
	s_barrier
	ds_read_b128 v[130:133], v242
	ds_read_b128 v[134:137], v242 offset:1024
	ds_read_b128 v[138:141], v242 offset:2048
	ds_read_b128 v[142:145], v242 offset:3072
	s_add_u32 s22, s22, s94
	s_addc_u32 s23, s23, 0
	s_mov_b32 m0, s84
	ds_read_b128 v[146:149], v218 offset:32768
	ds_read_b128 v[150:153], v218 offset:33792
	ds_read_b128 v[154:157], v218 offset:34816
	ds_read_b128 v[158:161], v218 offset:35840
	ds_read_b128 v[176:179], v218 offset:36864
	ds_read_b128 v[180:183], v218 offset:37888
	ds_read_b128 v[184:187], v218 offset:38912
	ds_read_b128 v[188:191], v218 offset:39936
	global_load_lds_dwordx4 v162, s[22:23]
	s_mov_b32 m0, s85
	s_nop 0
	global_load_lds_dwordx4 v166, s[22:23]
	s_waitcnt lgkmcnt(8)
	s_barrier
	s_waitcnt lgkmcnt(0)
	v_mfma_f32_16x16x32_bf16 v[126:129], v[130:133], v[146:149], v[126:129]
	v_mfma_f32_16x16x32_bf16 v[122:125], v[138:141], v[146:149], v[122:125]
	v_mfma_f32_16x16x32_bf16 v[118:121], v[130:133], v[154:157], v[118:121]
	v_mfma_f32_16x16x32_bf16 v[114:117], v[138:141], v[154:157], v[114:117]
	v_mfma_f32_16x16x32_bf16 v[102:105], v[130:133], v[176:179], v[102:105]
	v_mfma_f32_16x16x32_bf16 v[98:101], v[138:141], v[176:179], v[98:101]
	v_mfma_f32_16x16x32_bf16 v[86:89], v[130:133], v[184:187], v[86:89]
	v_mfma_f32_16x16x32_bf16 v[82:85], v[138:141], v[184:187], v[82:85]
	v_mfma_f32_16x16x32_bf16 v[126:129], v[134:137], v[150:153], v[126:129]
	v_mfma_f32_16x16x32_bf16 v[122:125], v[142:145], v[150:153], v[122:125]
	v_mfma_f32_16x16x32_bf16 v[118:121], v[134:137], v[158:161], v[118:121]
	v_mfma_f32_16x16x32_bf16 v[114:117], v[142:145], v[158:161], v[114:117]
	v_mfma_f32_16x16x32_bf16 v[102:105], v[134:137], v[180:183], v[102:105]
	v_mfma_f32_16x16x32_bf16 v[98:101], v[142:145], v[180:183], v[98:101]
	v_mfma_f32_16x16x32_bf16 v[86:89], v[134:137], v[188:191], v[86:89]
	v_mfma_f32_16x16x32_bf16 v[82:85], v[142:145], v[188:191], v[82:85]
	s_barrier
	s_add_i32 s22, s38, s79
	s_mov_b32 m0, s22
	ds_read_b128 v[192:195], v243
	ds_read_b128 v[196:199], v243 offset:1024
	ds_read_b128 v[200:203], v243 offset:2048
	ds_read_b128 v[204:207], v243 offset:3072
	global_load_lds_dwordx4 v164, s[98:99]
	s_add_i32 m0, s22, 0x2000
	s_nop 0
	global_load_lds_dwordx4 v170, s[98:99]
	s_add_u32 s98, s98, s94
	s_addc_u32 s99, s99, 0
	s_barrier
	s_waitcnt lgkmcnt(0)
	v_mfma_f32_16x16x32_bf16 v[110:113], v[192:195], v[146:149], v[110:113]
	v_mfma_f32_16x16x32_bf16 v[106:109], v[200:203], v[146:149], v[106:109]
	v_mfma_f32_16x16x32_bf16 v[94:97], v[192:195], v[154:157], v[94:97]
	v_mfma_f32_16x16x32_bf16 v[90:93], v[200:203], v[154:157], v[90:93]
	v_mfma_f32_16x16x32_bf16 v[78:81], v[192:195], v[176:179], v[78:81]
	v_mfma_f32_16x16x32_bf16 v[74:77], v[200:203], v[176:179], v[74:77]
	v_mfma_f32_16x16x32_bf16 v[70:73], v[192:195], v[184:187], v[70:73]
	v_mfma_f32_16x16x32_bf16 v[66:69], v[200:203], v[184:187], v[66:69]
	v_mfma_f32_16x16x32_bf16 v[110:113], v[196:199], v[150:153], v[110:113]
	v_mfma_f32_16x16x32_bf16 v[106:109], v[204:207], v[150:153], v[106:109]
	v_mfma_f32_16x16x32_bf16 v[94:97], v[196:199], v[158:161], v[94:97]
	v_mfma_f32_16x16x32_bf16 v[90:93], v[204:207], v[158:161], v[90:93]
	v_mfma_f32_16x16x32_bf16 v[78:81], v[196:199], v[180:183], v[78:81]
	v_mfma_f32_16x16x32_bf16 v[74:77], v[204:207], v[180:183], v[74:77]
	v_mfma_f32_16x16x32_bf16 v[70:73], v[196:199], v[188:191], v[70:73]
	v_mfma_f32_16x16x32_bf16 v[66:69], v[204:207], v[188:191], v[66:69]
	s_mov_b32 m0, s33
	s_barrier
	ds_read_b128 v[146:149], v218 offset:49152
	ds_read_b128 v[150:153], v218 offset:50176
	ds_read_b128 v[154:157], v218 offset:51200
	ds_read_b128 v[158:161], v218 offset:52224
	ds_read_b128 v[176:179], v218 offset:53248
	ds_read_b128 v[180:183], v218 offset:54272
	ds_read_b128 v[184:187], v218 offset:55296
	ds_read_b128 v[188:191], v218 offset:56320
	global_load_lds_dwordx4 v162, s[100:101]
	s_mov_b32 m0, s28
	s_nop 0
	global_load_lds_dwordx4 v166, s[100:101]
	s_barrier
	s_waitcnt lgkmcnt(0)
	v_mfma_f32_16x16x32_bf16 v[62:65], v[130:133], v[146:149], v[62:65]
	v_mfma_f32_16x16x32_bf16 v[58:61], v[138:141], v[146:149], v[58:61]
	v_mfma_f32_16x16x32_bf16 v[54:57], v[130:133], v[154:157], v[54:57]
	v_mfma_f32_16x16x32_bf16 v[50:53], v[138:141], v[154:157], v[50:53]
	v_mfma_f32_16x16x32_bf16 v[38:41], v[130:133], v[176:179], v[38:41]
	v_mfma_f32_16x16x32_bf16 v[34:37], v[138:141], v[176:179], v[34:37]
	v_mfma_f32_16x16x32_bf16 v[22:25], v[130:133], v[184:187], v[22:25]
	v_mfma_f32_16x16x32_bf16 v[18:21], v[138:141], v[184:187], v[18:21]
	v_mfma_f32_16x16x32_bf16 v[62:65], v[134:137], v[150:153], v[62:65]
	v_mfma_f32_16x16x32_bf16 v[58:61], v[142:145], v[150:153], v[58:61]
	v_mfma_f32_16x16x32_bf16 v[54:57], v[134:137], v[158:161], v[54:57]
	v_mfma_f32_16x16x32_bf16 v[50:53], v[142:145], v[158:161], v[50:53]
	v_mfma_f32_16x16x32_bf16 v[38:41], v[134:137], v[180:183], v[38:41]
	v_mfma_f32_16x16x32_bf16 v[34:37], v[142:145], v[180:183], v[34:37]
	v_mfma_f32_16x16x32_bf16 v[22:25], v[134:137], v[188:191], v[22:25]
	v_mfma_f32_16x16x32_bf16 v[18:21], v[142:145], v[188:191], v[18:21]
	s_barrier
; #define PG8_STAGE(bufoff, gbase, voff) do { _Pragma("unroll") for (int _i = 0; _i < 2; ++_i) \
;         __builtin_amdgcn_global_load_lds((const unsigned*)((const char*)(gbase) + (voff)[_i]), (PG8_LAS unsigned*)(lds + (bufoff) + ldsw + _i * 8192), 16, 0, 0); } while (0)
; #define PG8_LDA(dst, b, h) do { _Pragma("unroll") for (int m = 0; m < 4; ++m) _Pragma("unroll") for (int k = 0; k < 2; ++k) dst[m][k] = *(const PG8_LAS bf16x8*)(lds + PG8_SA(b, h) + aoff + m * 2048 + k * 1024); } while (0)
; #define PG8_LDB(dst, b, h) do { _Pragma("unroll") for (int n = 0; n < 2; ++n) _Pragma("unroll") for (int k = 0; k < 2; ++k) dst[n][k] = *(const PG8_LAS bf16x8*)(lds + PG8_SB(b, h) + boff + n * 2048 + k * 1024); } while (0)
; #define PG8_MMA(ai, bj, At, Bt) do { __builtin_amdgcn_s_setprio(1); _Pragma("unroll") for (int m = 0; m < 4; ++m) _Pragma("unroll") for (int n = 0; n < 2; ++n) _Pragma("unroll") for (int k = 0; k < 2; ++k) \
;         acc[ai][bj][m][n] = __builtin_amdgcn_mfma_f32_16x16x32_bf16(Bt[n][k], At[m][k], acc[ai][bj][m][n], 0, 0, 0); __builtin_amdgcn_s_setprio(0); } while (0)
; #define PG8_WAIT_V(n) asm volatile("s_waitcnt vmcnt(" #n ")" ::: "memory")
; #define PG8_WAIT_L(n) asm volatile("s_waitcnt lgkmcnt(" #n ")" ::: "memory")
; #define PG8_BAR __builtin_amdgcn_s_barrier()
; #define PG8_SCHED __builtin_amdgcn_sched_barrier(0)
; template <class Epi, class Sched, bool STAMP = false>
; __device__ __forceinline__ void gemm_phase(PG8_LAS unsigned char* lds, const Gemm g, const Sched& S, const Epi& E, unsigned long long* stamps) {
;     ...
;             PG8_LDB(B0, 0, 0); PG8_SCHED; PG8_LDA(At, 0, 0); PG8_STAGE(PG8_SA(1, 1), a1 + hstep, voffA);
;             PG8_WAIT_L(8); PG8_BAR; PG8_WAIT_L(0); PG8_MMA(0, 0, At, B0); PG8_BAR; PG8_SCHED;
;             PG8_LDB(B1, 0, 1); PG8_STAGE(PG8_SB(0, 0), b2, voffB);
;             PG8_BAR; PG8_WAIT_L(0); PG8_MMA(0, 1, At, B1); PG8_BAR;
;             PG8_LDA(At, 0, 1); PG8_STAGE(PG8_SA(0, 0), a2, voffA);
;     ...
;             PG8_STAGE(PG8_SB(1, 1), b3 + hstep, voffB);
;             PG8_WAIT_V(6); PG8_BAR; PG8_MMA(1, 1, At, B1); PG8_BAR;
	s_add_i32 s22, s35, s79
	s_mov_b32 m0, s22
	s_nop 0
	global_load_lds_dwordx4 v164, s[98:99]
	s_add_i32 m0, s22, 0x2000
	s_nop 0
	global_load_lds_dwordx4 v170, s[98:99]
	s_waitcnt vmcnt(6)
	s_barrier
	v_mfma_f32_16x16x32_bf16 v[46:49], v[192:195], v[146:149], v[46:49]
	v_mfma_f32_16x16x32_bf16 v[42:45], v[200:203], v[146:149], v[42:45]
	v_mfma_f32_16x16x32_bf16 v[30:33], v[192:195], v[154:157], v[30:33]
	v_mfma_f32_16x16x32_bf16 v[26:29], v[200:203], v[154:157], v[26:29]
	v_mfma_f32_16x16x32_bf16 v[14:17], v[192:195], v[176:179], v[14:17]
	v_mfma_f32_16x16x32_bf16 v[10:13], v[200:203], v[176:179], v[10:13]
	v_mfma_f32_16x16x32_bf16 v[6:9], v[192:195], v[184:187], v[6:9]
	v_mfma_f32_16x16x32_bf16 v[2:5], v[200:203], v[184:187], v[2:5]
	v_mfma_f32_16x16x32_bf16 v[46:49], v[196:199], v[150:153], v[46:49]
	v_mfma_f32_16x16x32_bf16 v[42:45], v[204:207], v[150:153], v[42:45]
	v_mfma_f32_16x16x32_bf16 v[30:33], v[196:199], v[158:161], v[30:33]
	v_mfma_f32_16x16x32_bf16 v[26:29], v[204:207], v[158:161], v[26:29]
	v_mfma_f32_16x16x32_bf16 v[14:17], v[196:199], v[180:183], v[14:17]
	v_mfma_f32_16x16x32_bf16 v[10:13], v[204:207], v[180:183], v[10:13]
	v_mfma_f32_16x16x32_bf16 v[6:9], v[196:199], v[188:191], v[6:9]
	v_mfma_f32_16x16x32_bf16 v[2:5], v[204:207], v[188:191], v[2:5]
	s_add_u32 s0, s0, 0x100
	s_addc_u32 s1, s1, 0
	s_add_u32 s88, s88, 0x100
	s_addc_u32 s89, s89, 0
	s_cmp_ge_u32 s93, s26
	s_mov_b32 s22, s93
	s_barrier
	s_cbranch_scc0 .LBB0_745
	s_branch .Lg_epi
.LBB0_745:
	s_add_i32 s93, s22, 2
	s_add_u32 s38, s0, 0x80
	s_addc_u32 s23, s1, 0
	s_add_i32 s62, 0, 0x10000
	ds_read_b128 v[130:133], v240
	ds_read_b128 v[134:137], v240 offset:1024
	ds_read_b128 v[138:141], v240 offset:2048
	ds_read_b128 v[142:145], v240 offset:3072
	s_cmp_eq_u32 s4, s22
	s_cselect_b32 s22, s90, s38
	s_cselect_b32 s23, s91, s23
	s_cselect_b32 s39, s31, s89
	s_cselect_b32 s38, s30, s88
	s_add_i32 m0, s80, 0xc000
	ds_read_b128 v[146:149], v218
	ds_read_b128 v[150:153], v218 offset:1024
	ds_read_b128 v[154:157], v218 offset:2048
	ds_read_b128 v[158:161], v218 offset:3072
	ds_read_b128 v[176:179], v218 offset:4096
	ds_read_b128 v[180:183], v218 offset:5120
	ds_read_b128 v[184:187], v218 offset:6144
	ds_read_b128 v[188:191], v218 offset:7168
	global_load_lds_dwordx4 v172, s[0:1]
	s_add_i32 m0, s80, 0xe000
	s_nop 0
	global_load_lds_dwordx4 v174, s[0:1]
	s_waitcnt lgkmcnt(8)
	s_barrier
	s_waitcnt lgkmcnt(0)
	v_mfma_f32_16x16x32_bf16 v[126:129], v[130:133], v[146:149], v[126:129]
	v_mfma_f32_16x16x32_bf16 v[122:125], v[138:141], v[146:149], v[122:125]
	v_mfma_f32_16x16x32_bf16 v[118:121], v[130:133], v[154:157], v[118:121]
	v_mfma_f32_16x16x32_bf16 v[114:117], v[138:141], v[154:157], v[114:117]
	v_mfma_f32_16x16x32_bf16 v[102:105], v[130:133], v[176:179], v[102:105]
	v_mfma_f32_16x16x32_bf16 v[98:101], v[138:141], v[176:179], v[98:101]
	v_mfma_f32_16x16x32_bf16 v[86:89], v[130:133], v[184:187], v[86:89]
	v_mfma_f32_16x16x32_bf16 v[82:85], v[138:141], v[184:187], v[82:85]
	v_mfma_f32_16x16x32_bf16 v[126:129], v[134:137], v[150:153], v[126:129]
	v_mfma_f32_16x16x32_bf16 v[122:125], v[142:145], v[150:153], v[122:125]
	v_mfma_f32_16x16x32_bf16 v[118:121], v[134:137], v[158:161], v[118:121]
	v_mfma_f32_16x16x32_bf16 v[114:117], v[142:145], v[158:161], v[114:117]
	v_mfma_f32_16x16x32_bf16 v[102:105], v[134:137], v[180:183], v[102:105]
	v_mfma_f32_16x16x32_bf16 v[98:101], v[142:145], v[180:183], v[98:101]
	v_mfma_f32_16x16x32_bf16 v[86:89], v[134:137], v[188:191], v[86:89]
	v_mfma_f32_16x16x32_bf16 v[82:85], v[142:145], v[188:191], v[82:85]
	s_barrier
	s_add_i32 s63, 0, 0x14000
	s_add_i32 s62, s62, s79
	s_add_u32 s98, s38, s10
	s_addc_u32 s99, s39, s11
	s_mov_b32 m0, s62
	ds_read_b128 v[192:195], v241
	ds_read_b128 v[196:199], v241 offset:1024
	ds_read_b128 v[200:203], v241 offset:2048
	ds_read_b128 v[204:207], v241 offset:3072
	global_load_lds_dwordx4 v164, s[38:39]
	s_add_i32 m0, s62, 0x2000
	s_nop 0
	global_load_lds_dwordx4 v170, s[38:39]
	s_barrier
	s_waitcnt lgkmcnt(0)
	v_mfma_f32_16x16x32_bf16 v[110:113], v[192:195], v[146:149], v[110:113]
	v_mfma_f32_16x16x32_bf16 v[106:109], v[200:203], v[146:149], v[106:109]
	v_mfma_f32_16x16x32_bf16 v[94:97], v[192:195], v[154:157], v[94:97]
	v_mfma_f32_16x16x32_bf16 v[90:93], v[200:203], v[154:157], v[90:93]
	v_mfma_f32_16x16x32_bf16 v[78:81], v[192:195], v[176:179], v[78:81]
	v_mfma_f32_16x16x32_bf16 v[74:77], v[200:203], v[176:179], v[74:77]
	v_mfma_f32_16x16x32_bf16 v[70:73], v[192:195], v[184:187], v[70:73]
	v_mfma_f32_16x16x32_bf16 v[66:69], v[200:203], v[184:187], v[66:69]
	v_mfma_f32_16x16x32_bf16 v[110:113], v[196:199], v[150:153], v[110:113]
	v_mfma_f32_16x16x32_bf16 v[106:109], v[204:207], v[150:153], v[106:109]
	v_mfma_f32_16x16x32_bf16 v[94:97], v[196:199], v[158:161], v[94:97]
	v_mfma_f32_16x16x32_bf16 v[90:93], v[204:207], v[158:161], v[90:93]
	v_mfma_f32_16x16x32_bf16 v[78:81], v[196:199], v[180:183], v[78:81]
	v_mfma_f32_16x16x32_bf16 v[74:77], v[204:207], v[180:183], v[74:77]
	v_mfma_f32_16x16x32_bf16 v[70:73], v[196:199], v[188:191], v[70:73]
	v_mfma_f32_16x16x32_bf16 v[66:69], v[204:207], v[188:191], v[66:69]
	s_mov_b32 m0, s80
	s_add_u32 s100, s22, s10
	s_addc_u32 s101, s23, s11
	s_barrier
	ds_read_b128 v[146:149], v218 offset:16384
	ds_read_b128 v[150:153], v218 offset:17408
	ds_read_b128 v[154:157], v218 offset:18432
	ds_read_b128 v[158:161], v218 offset:19456
	ds_read_b128 v[176:179], v218 offset:20480
	ds_read_b128 v[180:183], v218 offset:21504
	ds_read_b128 v[184:187], v218 offset:22528
	ds_read_b128 v[188:191], v218 offset:23552
	global_load_lds_dwordx4 v162, s[22:23]
	s_mov_b32 m0, s81
	s_nop 0
	global_load_lds_dwordx4 v166, s[22:23]
	s_barrier
; #define PG8_STAGE(bufoff, gbase, voff) do { _Pragma("unroll") for (int _i = 0; _i < 2; ++_i) \
;         __builtin_amdgcn_global_load_lds((const unsigned*)((const char*)(gbase) + (voff)[_i]), (PG8_LAS unsigned*)(lds + (bufoff) + ldsw + _i * 8192), 16, 0, 0); } while (0)
; #define PG8_LDA(dst, b, h) do { _Pragma("unroll") for (int m = 0; m < 4; ++m) _Pragma("unroll") for (int k = 0; k < 2; ++k) dst[m][k] = *(const PG8_LAS bf16x8*)(lds + PG8_SA(b, h) + aoff + m * 2048 + k * 1024); } while (0)
; #define PG8_LDB(dst, b, h) do { _Pragma("unroll") for (int n = 0; n < 2; ++n) _Pragma("unroll") for (int k = 0; k < 2; ++k) dst[n][k] = *(const PG8_LAS bf16x8*)(lds + PG8_SB(b, h) + boff + n * 2048 + k * 1024); } while (0)
; #define PG8_MMA(ai, bj, At, Bt) do { __builtin_amdgcn_s_setprio(1); _Pragma("unroll") for (int m = 0; m < 4; ++m) _Pragma("unroll") for (int n = 0; n < 2; ++n) _Pragma("unroll") for (int k = 0; k < 2; ++k) \
;         acc[ai][bj][m][n] = __builtin_amdgcn_mfma_f32_16x16x32_bf16(Bt[n][k], At[m][k], acc[ai][bj][m][n], 0, 0, 0); __builtin_amdgcn_s_setprio(0); } while (0)
; #define PG8_WAIT_V(n) asm volatile("s_waitcnt vmcnt(" #n ")" ::: "memory")
; #define PG8_WAIT_L(n) asm volatile("s_waitcnt lgkmcnt(" #n ")" ::: "memory")
; #define PG8_BAR __builtin_amdgcn_s_barrier()
; #define PG8_SCHED __builtin_amdgcn_sched_barrier(0)
; template <class Epi, class Sched, bool STAMP = false>
; __device__ __forceinline__ void gemm_phase(PG8_LAS unsigned char* lds, const Gemm g, const Sched& S, const Epi& E, unsigned long long* stamps) {
;     ...
;             PG8_BAR; PG8_WAIT_L(0); PG8_MMA(1, 0, At, B0); PG8_BAR; PG8_SCHED;
;             PG8_STAGE(PG8_SB(0, 1), b2 + hstep, voffB);
;             PG8_WAIT_V(6); PG8_BAR; PG8_MMA(1, 1, At, B1); PG8_BAR;
;             PG8_LDB(B0, 1, 0); PG8_SCHED; PG8_LDA(At, 1, 0); PG8_STAGE(PG8_SA(0, 1), a2 + hstep, voffA);
;             PG8_WAIT_L(8); PG8_BAR; PG8_WAIT_L(0); PG8_MMA(0, 0, At, B0); PG8_BAR; PG8_SCHED;
	s_waitcnt lgkmcnt(0)
	v_mfma_f32_16x16x32_bf16 v[62:65], v[130:133], v[146:149], v[62:65]
	v_mfma_f32_16x16x32_bf16 v[58:61], v[138:141], v[146:149], v[58:61]
	v_mfma_f32_16x16x32_bf16 v[54:57], v[130:133], v[154:157], v[54:57]
	v_mfma_f32_16x16x32_bf16 v[50:53], v[138:141], v[154:157], v[50:53]
	v_mfma_f32_16x16x32_bf16 v[38:41], v[130:133], v[176:179], v[38:41]
	v_mfma_f32_16x16x32_bf16 v[34:37], v[138:141], v[176:179], v[34:37]
	v_mfma_f32_16x16x32_bf16 v[22:25], v[130:133], v[184:187], v[22:25]
	v_mfma_f32_16x16x32_bf16 v[18:21], v[138:141], v[184:187], v[18:21]
	v_mfma_f32_16x16x32_bf16 v[62:65], v[134:137], v[150:153], v[62:65]
	v_mfma_f32_16x16x32_bf16 v[58:61], v[142:145], v[150:153], v[58:61]
	v_mfma_f32_16x16x32_bf16 v[54:57], v[134:137], v[158:161], v[54:57]
	v_mfma_f32_16x16x32_bf16 v[50:53], v[142:145], v[158:161], v[50:53]
	v_mfma_f32_16x16x32_bf16 v[38:41], v[134:137], v[180:183], v[38:41]
	v_mfma_f32_16x16x32_bf16 v[34:37], v[142:145], v[180:183], v[34:37]
	v_mfma_f32_16x16x32_bf16 v[22:25], v[134:137], v[188:191], v[22:25]
	v_mfma_f32_16x16x32_bf16 v[18:21], v[142:145], v[188:191], v[18:21]
	s_barrier
	s_add_u32 s38, s38, s94
	s_addc_u32 s39, s39, 0
	s_add_i32 s62, s63, s79
	s_mov_b32 m0, s62
	global_load_lds_dwordx4 v164, s[38:39]
	s_add_i32 m0, s62, 0x2000
	s_nop 0
	global_load_lds_dwordx4 v170, s[38:39]
	s_waitcnt vmcnt(6)
	s_barrier
	v_mfma_f32_16x16x32_bf16 v[46:49], v[192:195], v[146:149], v[46:49]
	v_mfma_f32_16x16x32_bf16 v[42:45], v[200:203], v[146:149], v[42:45]
	v_mfma_f32_16x16x32_bf16 v[30:33], v[192:195], v[154:157], v[30:33]
	v_mfma_f32_16x16x32_bf16 v[26:29], v[200:203], v[154:157], v[26:29]
	v_mfma_f32_16x16x32_bf16 v[14:17], v[192:195], v[176:179], v[14:17]
	v_mfma_f32_16x16x32_bf16 v[10:13], v[200:203], v[176:179], v[10:13]
	v_mfma_f32_16x16x32_bf16 v[6:9], v[192:195], v[184:187], v[6:9]
	v_mfma_f32_16x16x32_bf16 v[2:5], v[200:203], v[184:187], v[2:5]
	v_mfma_f32_16x16x32_bf16 v[46:49], v[196:199], v[150:153], v[46:49]
	v_mfma_f32_16x16x32_bf16 v[42:45], v[204:207], v[150:153], v[42:45]
	v_mfma_f32_16x16x32_bf16 v[30:33], v[196:199], v[158:161], v[30:33]
	v_mfma_f32_16x16x32_bf16 v[26:29], v[204:207], v[158:161], v[26:29]
	v_mfma_f32_16x16x32_bf16 v[14:17], v[196:199], v[180:183], v[14:17]
	v_mfma_f32_16x16x32_bf16 v[10:13], v[204:207], v[180:183], v[10:13]
	v_mfma_f32_16x16x32_bf16 v[6:9], v[196:199], v[188:191], v[6:9]
	v_mfma_f32_16x16x32_bf16 v[2:5], v[204:207], v[188:191], v[2:5]
	s_add_i32 s38, 0, 0x18000
	s_barrier
	ds_read_b128 v[130:133], v242
	ds_read_b128 v[134:137], v242 offset:1024
	ds_read_b128 v[138:141], v242 offset:2048
	ds_read_b128 v[142:145], v242 offset:3072
	s_add_u32 s22, s22, s94
	s_addc_u32 s23, s23, 0
	s_mov_b32 m0, s84
	ds_read_b128 v[146:149], v218 offset:32768
	ds_read_b128 v[150:153], v218 offset:33792
	ds_read_b128 v[154:157], v218 offset:34816
	ds_read_b128 v[158:161], v218 offset:35840
	ds_read_b128 v[176:179], v218 offset:36864
	ds_read_b128 v[180:183], v218 offset:37888
	ds_read_b128 v[184:187], v218 offset:38912
	ds_read_b128 v[188:191], v218 offset:39936
	global_load_lds_dwordx4 v162, s[22:23]
	s_mov_b32 m0, s85
	s_nop 0
	global_load_lds_dwordx4 v166, s[22:23]
	s_waitcnt lgkmcnt(8)
	s_barrier
	s_waitcnt lgkmcnt(0)
	v_mfma_f32_16x16x32_bf16 v[126:129], v[130:133], v[146:149], v[126:129]
	v_mfma_f32_16x16x32_bf16 v[122:125], v[138:141], v[146:149], v[122:125]
	v_mfma_f32_16x16x32_bf16 v[118:121], v[130:133], v[154:157], v[118:121]
	v_mfma_f32_16x16x32_bf16 v[114:117], v[138:141], v[154:157], v[114:117]
	v_mfma_f32_16x16x32_bf16 v[102:105], v[130:133], v[176:179], v[102:105]
	v_mfma_f32_16x16x32_bf16 v[98:101], v[138:141], v[176:179], v[98:101]
	v_mfma_f32_16x16x32_bf16 v[86:89], v[130:133], v[184:187], v[86:89]
	v_mfma_f32_16x16x32_bf16 v[82:85], v[138:141], v[184:187], v[82:85]
	v_mfma_f32_16x16x32_bf16 v[126:129], v[134:137], v[150:153], v[126:129]
	v_mfma_f32_16x16x32_bf16 v[122:125], v[142:145], v[150:153], v[122:125]
	v_mfma_f32_16x16x32_bf16 v[118:121], v[134:137], v[158:161], v[118:121]
	v_mfma_f32_16x16x32_bf16 v[114:117], v[142:145], v[158:161], v[114:117]
	v_mfma_f32_16x16x32_bf16 v[102:105], v[134:137], v[180:183], v[102:105]
	v_mfma_f32_16x16x32_bf16 v[98:101], v[142:145], v[180:183], v[98:101]
	v_mfma_f32_16x16x32_bf16 v[86:89], v[134:137], v[188:191], v[86:89]
	v_mfma_f32_16x16x32_bf16 v[82:85], v[142:145], v[188:191], v[82:85]
	s_barrier
; #define PG8_STAGE(bufoff, gbase, voff) do { _Pragma("unroll") for (int _i = 0; _i < 2; ++_i) \
;         __builtin_amdgcn_global_load_lds((const unsigned*)((const char*)(gbase) + (voff)[_i]), (PG8_LAS unsigned*)(lds + (bufoff) + ldsw + _i * 8192), 16, 0, 0); } while (0)
; #define PG8_LDA(dst, b, h) do { _Pragma("unroll") for (int m = 0; m < 4; ++m) _Pragma("unroll") for (int k = 0; k < 2; ++k) dst[m][k] = *(const PG8_LAS bf16x8*)(lds + PG8_SA(b, h) + aoff + m * 2048 + k * 1024); } while (0)
; #define PG8_LDB(dst, b, h) do { _Pragma("unroll") for (int n = 0; n < 2; ++n) _Pragma("unroll") for (int k = 0; k < 2; ++k) dst[n][k] = *(const PG8_LAS bf16x8*)(lds + PG8_SB(b, h) + boff + n * 2048 + k * 1024); } while (0)
; #define PG8_MMA(ai, bj, At, Bt) do { __builtin_amdgcn_s_setprio(1); _Pragma("unroll") for (int m = 0; m < 4; ++m) _Pragma("unroll") for (int n = 0; n < 2; ++n) _Pragma("unroll") for (int k = 0; k < 2; ++k) \
;         acc[ai][bj][m][n] = __builtin_amdgcn_mfma_f32_16x16x32_bf16(Bt[n][k], At[m][k], acc[ai][bj][m][n], 0, 0, 0); __builtin_amdgcn_s_setprio(0); } while (0)
; #define PG8_WAIT_V(n) asm volatile("s_waitcnt vmcnt(" #n ")" ::: "memory")
; #define PG8_WAIT_L(n) asm volatile("s_waitcnt lgkmcnt(" #n ")" ::: "memory")
; #define PG8_BAR __builtin_amdgcn_s_barrier()
; #define PG8_SCHED __builtin_amdgcn_sched_barrier(0)
; template <class Epi, class Sched, bool STAMP = false>
; __device__ __forceinline__ void gemm_phase(PG8_LAS unsigned char* lds, const Gemm g, const Sched& S, const Epi& E, unsigned long long* stamps) {
;     ...
;             PG8_LDB(B1, 1, 1); PG8_STAGE(PG8_SB(1, 0), b3, voffB);
;             PG8_BAR; PG8_WAIT_L(0); PG8_MMA(0, 1, At, B1); PG8_BAR;
;             PG8_LDA(At, 1, 1); PG8_STAGE(PG8_SA(1, 0), a3, voffA);
;             PG8_BAR; PG8_WAIT_L(0); PG8_MMA(1, 0, At, B0); PG8_BAR; PG8_SCHED;
;             PG8_STAGE(PG8_SB(1, 1), b3 + hstep, voffB);
;             PG8_WAIT_V(6); PG8_BAR; PG8_MMA(1, 1, At, B1); PG8_BAR;
;         }
	s_add_i32 s22, s38, s79
	s_mov_b32 m0, s22
	ds_read_b128 v[192:195], v243
	ds_read_b128 v[196:199], v243 offset:1024
	ds_read_b128 v[200:203], v243 offset:2048
	ds_read_b128 v[204:207], v243 offset:3072
	global_load_lds_dwordx4 v164, s[98:99]
	s_add_i32 m0, s22, 0x2000
	s_nop 0
	global_load_lds_dwordx4 v170, s[98:99]
	s_add_u32 s98, s98, s94
	s_addc_u32 s99, s99, 0
	s_barrier
	s_waitcnt lgkmcnt(0)
	v_mfma_f32_16x16x32_bf16 v[110:113], v[192:195], v[146:149], v[110:113]
	v_mfma_f32_16x16x32_bf16 v[106:109], v[200:203], v[146:149], v[106:109]
	v_mfma_f32_16x16x32_bf16 v[94:97], v[192:195], v[154:157], v[94:97]
	v_mfma_f32_16x16x32_bf16 v[90:93], v[200:203], v[154:157], v[90:93]
	v_mfma_f32_16x16x32_bf16 v[78:81], v[192:195], v[176:179], v[78:81]
	v_mfma_f32_16x16x32_bf16 v[74:77], v[200:203], v[176:179], v[74:77]
	v_mfma_f32_16x16x32_bf16 v[70:73], v[192:195], v[184:187], v[70:73]
	v_mfma_f32_16x16x32_bf16 v[66:69], v[200:203], v[184:187], v[66:69]
	v_mfma_f32_16x16x32_bf16 v[110:113], v[196:199], v[150:153], v[110:113]
	v_mfma_f32_16x16x32_bf16 v[106:109], v[204:207], v[150:153], v[106:109]
	v_mfma_f32_16x16x32_bf16 v[94:97], v[196:199], v[158:161], v[94:97]
	v_mfma_f32_16x16x32_bf16 v[90:93], v[204:207], v[158:161], v[90:93]
	v_mfma_f32_16x16x32_bf16 v[78:81], v[196:199], v[180:183], v[78:81]
	v_mfma_f32_16x16x32_bf16 v[74:77], v[204:207], v[180:183], v[74:77]
	v_mfma_f32_16x16x32_bf16 v[70:73], v[196:199], v[188:191], v[70:73]
	v_mfma_f32_16x16x32_bf16 v[66:69], v[204:207], v[188:191], v[66:69]
	s_mov_b32 m0, s33
	s_barrier
	ds_read_b128 v[146:149], v218 offset:49152
	ds_read_b128 v[150:153], v218 offset:50176
	ds_read_b128 v[154:157], v218 offset:51200
	ds_read_b128 v[158:161], v218 offset:52224
	ds_read_b128 v[176:179], v218 offset:53248
	ds_read_b128 v[180:183], v218 offset:54272
	ds_read_b128 v[184:187], v218 offset:55296
	ds_read_b128 v[188:191], v218 offset:56320
	global_load_lds_dwordx4 v162, s[100:101]
	s_mov_b32 m0, s28
	s_nop 0
	global_load_lds_dwordx4 v166, s[100:101]
	s_barrier
	s_waitcnt lgkmcnt(0)
	v_mfma_f32_16x16x32_bf16 v[62:65], v[130:133], v[146:149], v[62:65]
	v_mfma_f32_16x16x32_bf16 v[58:61], v[138:141], v[146:149], v[58:61]
	v_mfma_f32_16x16x32_bf16 v[54:57], v[130:133], v[154:157], v[54:57]
	v_mfma_f32_16x16x32_bf16 v[50:53], v[138:141], v[154:157], v[50:53]
	v_mfma_f32_16x16x32_bf16 v[38:41], v[130:133], v[176:179], v[38:41]
	v_mfma_f32_16x16x32_bf16 v[34:37], v[138:141], v[176:179], v[34:37]
	v_mfma_f32_16x16x32_bf16 v[22:25], v[130:133], v[184:187], v[22:25]
	v_mfma_f32_16x16x32_bf16 v[18:21], v[138:141], v[184:187], v[18:21]
	v_mfma_f32_16x16x32_bf16 v[62:65], v[134:137], v[150:153], v[62:65]
	v_mfma_f32_16x16x32_bf16 v[58:61], v[142:145], v[150:153], v[58:61]
	v_mfma_f32_16x16x32_bf16 v[54:57], v[134:137], v[158:161], v[54:57]
	v_mfma_f32_16x16x32_bf16 v[50:53], v[142:145], v[158:161], v[50:53]
	v_mfma_f32_16x16x32_bf16 v[38:41], v[134:137], v[180:183], v[38:41]
	v_mfma_f32_16x16x32_bf16 v[34:37], v[142:145], v[180:183], v[34:37]
	v_mfma_f32_16x16x32_bf16 v[22:25], v[134:137], v[188:191], v[22:25]
	v_mfma_f32_16x16x32_bf16 v[18:21], v[142:145], v[188:191], v[18:21]
	s_barrier
	s_add_i32 s22, s35, s79
	s_mov_b32 m0, s22
	s_nop 0
	global_load_lds_dwordx4 v164, s[98:99]
	s_add_i32 m0, s22, 0x2000
	s_nop 0
	global_load_lds_dwordx4 v170, s[98:99]
	s_waitcnt vmcnt(6)
	s_barrier
	v_mfma_f32_16x16x32_bf16 v[46:49], v[192:195], v[146:149], v[46:49]
	v_mfma_f32_16x16x32_bf16 v[42:45], v[200:203], v[146:149], v[42:45]
	v_mfma_f32_16x16x32_bf16 v[30:33], v[192:195], v[154:157], v[30:33]
	v_mfma_f32_16x16x32_bf16 v[26:29], v[200:203], v[154:157], v[26:29]
	v_mfma_f32_16x16x32_bf16 v[14:17], v[192:195], v[176:179], v[14:17]
	v_mfma_f32_16x16x32_bf16 v[10:13], v[200:203], v[176:179], v[10:13]
	v_mfma_f32_16x16x32_bf16 v[6:9], v[192:195], v[184:187], v[6:9]
	v_mfma_f32_16x16x32_bf16 v[2:5], v[200:203], v[184:187], v[2:5]
	v_mfma_f32_16x16x32_bf16 v[46:49], v[196:199], v[150:153], v[46:49]
	v_mfma_f32_16x16x32_bf16 v[42:45], v[204:207], v[150:153], v[42:45]
	v_mfma_f32_16x16x32_bf16 v[30:33], v[196:199], v[158:161], v[30:33]
	v_mfma_f32_16x16x32_bf16 v[26:29], v[204:207], v[158:161], v[26:29]
	v_mfma_f32_16x16x32_bf16 v[14:17], v[196:199], v[180:183], v[14:17]
	v_mfma_f32_16x16x32_bf16 v[10:13], v[204:207], v[180:183], v[10:13]
	v_mfma_f32_16x16x32_bf16 v[6:9], v[196:199], v[188:191], v[6:9]
	v_mfma_f32_16x16x32_bf16 v[2:5], v[204:207], v[188:191], v[2:5]
	s_add_u32 s0, s0, 0x100
	s_addc_u32 s1, s1, 0
	s_add_u32 s88, s88, 0x100
	s_addc_u32 s89, s89, 0
	s_cmp_ge_u32 s93, s26
	s_mov_b32 s22, s93
	s_barrier
	s_cbranch_scc0 .LBB0_745
